# conv tile split index 3072 (more slack for the conversion workgroups in scan pass C)
# baseline (speedup 1.0000x reference)
.LBB0_469:
	s_add_i32 s0, s33, 0xffffff10
	s_cmpk_gt_u32 s0, 0x91f
	s_cbranch_scc1 .LBB0_492
	v_lshlrev_b32_e32 v2, 2, v1
	v_lshrrev_b32_e32 v3, 3, v188
	v_add_u32_e32 v39, 0, v2
	v_readlane_b32 s8, v254, 0
	v_and_b32_e32 v26, 0x78, v3
	v_or_b32_e32 v33, 7, v3
	v_lshl_add_u32 v3, v1, 8, v39
	v_readlane_b32 s9, v254, 1
	v_readlane_b32 s10, v254, 2
	v_readlane_b32 s11, v254, 3
	v_readlane_b32 s12, v254, 4
	v_readlane_b32 s13, v254, 5
	v_lshl_add_u32 v34, v26, 2, v3
	v_lshl_add_u32 v35, v33, 2, v3
	v_mov_b32_e32 v3, 0
	v_readlane_b32 s14, v254, 6
	v_readlane_b32 s15, v254, 7
	s_mov_b64 s[6:7], s[10:11]
	s_mov_b64 s[8:9], s[12:13]
	v_lshl_add_u64 v[4:5], s[8:9], 0, v[2:3]
	v_lshl_add_u64 v[6:7], s[72:73], 0, v[2:3]
	v_lshl_add_u64 v[8:9], s[70:71], 0, v[2:3]
	v_lshl_add_u64 v[10:11], s[68:69], 0, v[2:3]
	v_lshl_add_u64 v[12:13], s[6:7], 0, v[2:3]
	v_lshl_add_u64 v[14:15], s[74:75], 0, v[2:3]
	v_lshlrev_b32_e32 v2, 1, v1
	v_lshl_add_u64 v[16:17], s[86:87], 0, v[2:3]
	s_mov_b64 s[2:3], 0x1880000
	v_lshl_add_u64 v[18:19], v[16:17], 0, s[2:3]
	s_mov_b64 s[2:3], 0x1300000
	s_add_i32 s4, s33, 0x1f0
	v_mul_u32_u24_e32 v38, 0x104, v26
	s_mov_b64 s[10:11], s[14:15]
	v_lshl_add_u64 v[20:21], v[16:17], 0, s[2:3]
	s_mov_b64 s[2:3], 0x800000
	v_mul_u32_u24_e32 v40, 0x104, v33
	v_lshl_add_u64 v[22:23], v[16:17], 0, s[2:3]
	s_mov_b64 s[2:3], 0x600000
	s_lshl_b32 s6, s50, 6
	s_mul_i32 s8, s50, 0x2e000
	v_lshrrev_b32_e32 v2, 6, v188
	s_lshl_b32 s0, s4, 2
	s_lshl_b32 s10, s50, 2
	v_add_u32_e32 v38, v39, v38
	s_mov_b32 s1, 0
	v_or_b32_e32 v27, 1, v26
	v_or_b32_e32 v28, 2, v26
	v_or_b32_e32 v29, 3, v26
	v_or_b32_e32 v30, 4, v26
	v_or_b32_e32 v31, 5, v26
	v_or_b32_e32 v32, 6, v26
	v_lshl_add_u64 v[24:25], v[16:17], 0, s[2:3]
	s_lshl_b32 s5, s4, 6
	s_addk_i32 s6, 0xc400
	v_mul_u32_u24_e32 v36, 0xb80, v33
	s_mul_i32 s7, s4, 0x2e000
	s_add_i32 s8, s8, 0xfd4e0000
	v_mul_u32_u24_e32 v37, 0x5c00, v2
	s_add_i32 s9, s0, 0x3cf80
	s_addk_i32 s10, 0xfc40
	v_add_u32_e32 v39, v39, v40
	s_movk_i32 s11, 0x7fff
	s_mov_b32 s12, 0xfff00
	s_mov_b32 s13, 0x40000
	v_add_u32_e32 v40, 0x400, v38
	s_branch .LBB0_472
.LBB0_471:
	s_add_i32 s4, s4, s95
	s_add_i32 s5, s5, s6
	s_add_i32 s7, s7, s8
	s_add_i32 s9, s9, s10
	s_cmpk_lt_i32 s4, 0xc00
	s_cbranch_scc0 .LBB0_492

.LBB0_731:
	s_add_i32 s0, s33, 0xffffff10
	s_cmpk_gt_u32 s0, 0xc5f
	s_cbranch_scc1 .LBB0_770
	v_lshlrev_b32_e32 v2, 2, v1
	v_lshrrev_b32_e32 v3, 3, v188
	v_add_u32_e32 v52, 0, v2
	v_and_b32_e32 v40, 0x78, v3
	v_or_b32_e32 v47, 7, v3
	v_lshl_add_u32 v3, v1, 8, v52
	v_readlane_b32 s12, v254, 0
	v_lshl_add_u32 v48, v40, 2, v3
	v_lshl_add_u32 v49, v47, 2, v3
	v_mov_b32_e32 v3, 0
	v_readlane_b32 s14, v254, 2
	v_readlane_b32 s15, v254, 3
	v_readlane_b32 s16, v254, 4
	v_readlane_b32 s17, v254, 5
	v_lshl_add_u64 v[4:5], s[84:85], 0, v[2:3]
	v_lshl_add_u64 v[8:9], s[72:73], 0, v[2:3]
	v_lshl_add_u64 v[6:7], s[16:17], 0, v[2:3]
	v_lshl_add_u64 v[10:11], s[70:71], 0, v[2:3]
	v_lshl_add_u64 v[12:13], s[68:69], 0, v[2:3]
	v_lshl_add_u64 v[14:15], s[14:15], 0, v[2:3]
	v_lshl_add_u64 v[16:17], s[74:75], 0, v[2:3]
	v_lshlrev_b32_e32 v2, 1, v1
	s_mov_b64 s[2:3], 0xb00000
	v_lshl_add_u64 v[18:19], s[86:87], 0, v[2:3]
	v_lshl_add_u64 v[20:21], v[8:9], 0, s[2:3]
	v_lshl_add_u64 v[24:25], v[10:11], 0, s[2:3]
	v_lshl_add_u64 v[28:29], v[12:13], 0, s[2:3]
	s_mov_b64 s[2:3], 0x1e80000
	v_lshl_add_u64 v[30:31], v[18:19], 0, s[2:3]
	s_mov_b64 s[2:3], 0x1880000
	s_mov_b64 s[6:7], 0x2b80000
	v_lshl_add_u64 v[32:33], v[18:19], 0, s[2:3]
	s_mov_b64 s[2:3], 0x1300000
	s_add_i32 s4, s33, 0xb10
	v_mul_u32_u24_e32 v51, 0x104, v40
	v_readlane_b32 s13, v254, 1
	v_lshl_add_u64 v[22:23], v[18:19], 0, s[6:7]
	s_mov_b64 s[6:7], 0x2080000
	v_lshl_add_u64 v[34:35], v[18:19], 0, s[2:3]
	s_mov_b64 s[2:3], 0x800000
	v_mul_u32_u24_e32 v53, 0x104, v47
	v_lshl_add_u64 v[26:27], v[18:19], 0, s[6:7]
	v_lshl_add_u64 v[36:37], v[18:19], 0, s[2:3]
	s_mov_b64 s[2:3], 0x600000
	s_lshl_b32 s7, s50, 6
	s_mul_i32 s9, s50, 0x2e000
	v_lshrrev_b32_e32 v2, 6, v188
	s_lshl_b32 s0, s4, 2
	s_lshl_b32 s13, s50, 2
	v_add_u32_e32 v51, v52, v51
	s_mov_b32 s1, 0
	v_or_b32_e32 v41, 1, v40
	v_or_b32_e32 v42, 2, v40
	v_or_b32_e32 v43, 3, v40
	v_or_b32_e32 v44, 4, v40
	v_or_b32_e32 v45, 5, v40
	v_or_b32_e32 v46, 6, v40
	s_add_i32 s5, s50, 0xffffff10
	v_lshl_add_u64 v[38:39], v[18:19], 0, s[2:3]
	s_lshl_b32 s6, s4, 6
	s_addk_i32 s7, 0xc400
	v_mul_u32_u24_e32 v1, 0xb80, v47
	s_mul_i32 s8, s4, 0x2e000
	s_add_i32 s9, s9, 0xfd4e0000
	v_mul_u32_u24_e32 v50, 0x5c00, v2
	s_add_i32 s12, s0, 0x3b480
	s_addk_i32 s13, 0xfc40
	v_add_u32_e32 v52, v52, v53
	s_movk_i32 s14, 0x7fff
	s_mov_b32 s15, 0xfff00
	s_mov_b32 s16, 0x40000
	v_add_u32_e32 v53, 0x400, v51
	v_readlane_b32 s18, v254, 6
	v_readlane_b32 s19, v254, 7
	s_branch .LBB0_734
